# v42 plus attention-B epilogue normalisation: 16 serialized LDS row-sum reads issued up front, counted lgkmcnt
# speedup vs baseline: 1.0169x; 1.0029x over previous
; template <int LD> ...
;     ...
;   float* stg = (float*)(lds + wv * 16384);
;   unsigned wb = (unsigned)(4 * hi * 128 + r32); asm volatile("" : "+v"(wb));
; #pragma unroll
;   for (int r = 0; r < 16; ++r) { const unsigned cr = (r & 3) + 8 * (r >> 2);
;     const float rs = __builtin_amdgcn_rsqf((ss[r] + xs[(wv ^ 1) * 32 + cr + 4 * hi]) * (1.f / 256.f) + EPS) * epi.oscale;
; #pragma unroll
;     for (int d0 = 0; d0 < 4; ++d0) stg[wb + cr * 128 + d0 * 32] = o[d0][r] * rs; }
.LBB0_28:
	s_or_b64 exec, exec, s[52:53]
	v_lshl_or_b32 v124, v216, 9, v215
	v_add_u32_e32 v125, s42, v178
	s_waitcnt lgkmcnt(0)
	s_barrier
	ds_read_b32 v232, v125
	ds_read_b32 v233, v125 offset:4
	ds_read_b32 v234, v125 offset:8
	ds_read_b32 v235, v125 offset:12
	ds_read_b32 v236, v125 offset:32
	ds_read_b32 v237, v125 offset:36
	ds_read_b32 v238, v125 offset:40
	ds_read_b32 v239, v125 offset:44
	ds_read_b32 v240, v125 offset:64
	ds_read_b32 v242, v125 offset:68
	ds_read_b32 v244, v125 offset:72
	ds_read_b32 v245, v125 offset:76
	ds_read_b32 v246, v125 offset:96
	ds_read_b32 v247, v125 offset:100
	ds_read_b32 v248, v125 offset:104
	s_waitcnt lgkmcnt(14)
	ds_read_b32 v249, v125 offset:108
	v_lshl_add_u32 v124, v124, 2, s41
	v_lshlrev_b32_e32 v160, 3, v214
	s_movk_i32 s24, 0xe800
	v_add_f32_e32 v64, v64, v232
	v_fmamk_f32 v64, v64, 0x3b800000, v203
	v_rsq_f32_e32 v64, v64
	s_nop 0
	v_mul_f32_e32 v64, v212, v64
	v_mul_f32_e32 v106, v106, v64
	v_mul_f32_e32 v108, v108, v64
	s_waitcnt lgkmcnt(14)
	ds_write2_b32 v124, v106, v108 offset1:32
	v_mul_f32_e32 v106, v114, v64
	v_mul_f32_e32 v64, v122, v64
	s_waitcnt lgkmcnt(14)
	ds_write2_b32 v124, v106, v64 offset0:64 offset1:96
	v_add_f32_e32 v64, v65, v233
	v_fmamk_f32 v64, v64, 0x3b800000, v203
	v_rsq_f32_e32 v64, v64
	s_nop 0
	v_mul_f32_e32 v64, v212, v64
	v_mul_f32_e32 v65, v107, v64
	v_mul_f32_e32 v106, v109, v64
	v_mul_f32_e32 v107, v115, v64
	v_mul_f32_e32 v64, v123, v64
	s_waitcnt lgkmcnt(14)
	ds_write2_b32 v124, v65, v106 offset0:128 offset1:160
	s_waitcnt lgkmcnt(14)
	ds_write2_b32 v124, v107, v64 offset0:192 offset1:224
	v_add_u32_e32 v65, 0x400, v124
	v_add_f32_e32 v64, v66, v234
	v_fmamk_f32 v64, v64, 0x3b800000, v203
	v_rsq_f32_e32 v64, v64
	s_nop 0
	v_mul_f32_e32 v64, v212, v64
	v_mul_f32_e32 v66, v118, v64
	v_mul_f32_e32 v106, v120, v64
	v_mul_f32_e32 v107, v166, v64
	v_mul_f32_e32 v64, v168, v64
	s_waitcnt lgkmcnt(14)
	ds_write2_b32 v65, v66, v106 offset1:32
	s_waitcnt lgkmcnt(14)
	ds_write2_b32 v65, v107, v64 offset0:64 offset1:96
	v_add_f32_e32 v64, v67, v235
	v_fmamk_f32 v64, v64, 0x3b800000, v203
	v_rsq_f32_e32 v64, v64
	s_nop 0
	v_mul_f32_e32 v64, v212, v64
	v_mul_f32_e32 v66, v119, v64
	v_mul_f32_e32 v67, v121, v64
	v_mul_f32_e32 v106, v167, v64
	v_mul_f32_e32 v64, v169, v64
	s_waitcnt lgkmcnt(14)
	ds_write2_b32 v65, v66, v67 offset0:128 offset1:160
	s_waitcnt lgkmcnt(14)
	ds_write2_b32 v65, v106, v64 offset0:192 offset1:224
	v_add_u32_e32 v65, 0x1000, v124
	v_add_f32_e32 v64, v72, v236
	v_fmamk_f32 v64, v64, 0x3b800000, v203
	v_rsq_f32_e32 v64, v64
	s_nop 0
	v_mul_f32_e32 v64, v212, v64
	v_mul_f32_e32 v66, v150, v64
	v_mul_f32_e32 v67, v152, v64
	v_mul_f32_e32 v72, v170, v64
	v_mul_f32_e32 v64, v172, v64
	s_waitcnt lgkmcnt(14)
	ds_write2_b32 v65, v66, v67 offset1:32
	s_waitcnt lgkmcnt(14)
	ds_write2_b32 v65, v72, v64 offset0:64 offset1:96
	v_add_f32_e32 v64, v73, v237
	v_fmamk_f32 v64, v64, 0x3b800000, v203
	v_rsq_f32_e32 v64, v64
	s_nop 0
	v_mul_f32_e32 v64, v212, v64
	v_mul_f32_e32 v66, v151, v64
	v_mul_f32_e32 v67, v153, v64
	v_mul_f32_e32 v72, v171, v64
	v_mul_f32_e32 v64, v173, v64
	s_waitcnt lgkmcnt(14)
	ds_write2_b32 v65, v66, v67 offset0:128 offset1:160
	s_waitcnt lgkmcnt(14)
	ds_write2_b32 v65, v72, v64 offset0:192 offset1:224
	v_add_u32_e32 v65, 0x1400, v124
	v_add_f32_e32 v64, v74, v238
	v_fmamk_f32 v64, v64, 0x3b800000, v203
	v_rsq_f32_e32 v64, v64
	s_nop 0
	v_mul_f32_e32 v64, v212, v64
	v_mul_f32_e32 v66, v138, v64
	v_mul_f32_e32 v67, v140, v64
	v_mul_f32_e32 v72, v154, v64
	v_mul_f32_e32 v64, v156, v64
	s_waitcnt lgkmcnt(14)
	ds_write2_b32 v65, v66, v67 offset1:32
	s_waitcnt lgkmcnt(14)
	ds_write2_b32 v65, v72, v64 offset0:64 offset1:96
	v_add_f32_e32 v64, v75, v239
	v_fmamk_f32 v64, v64, 0x3b800000, v203
	v_rsq_f32_e32 v64, v64
	s_nop 0
	v_mul_f32_e32 v64, v212, v64
	v_mul_f32_e32 v66, v139, v64
	v_mul_f32_e32 v67, v141, v64
	v_mul_f32_e32 v72, v155, v64
	v_mul_f32_e32 v64, v157, v64
	s_waitcnt lgkmcnt(14)
	ds_write2_b32 v65, v66, v67 offset0:128 offset1:160
	s_waitcnt lgkmcnt(14)
	ds_write2_b32 v65, v72, v64 offset0:192 offset1:224
	v_add_u32_e32 v65, 0x2000, v124
	v_add_f32_e32 v64, v76, v240
	v_fmamk_f32 v64, v64, 0x3b800000, v203
	v_rsq_f32_e32 v64, v64
	s_nop 0
	v_mul_f32_e32 v64, v212, v64
	v_mul_f32_e32 v66, v130, v64
	v_mul_f32_e32 v67, v144, v64
	v_mul_f32_e32 v72, v146, v64
	v_mul_f32_e32 v64, v158, v64
	s_waitcnt lgkmcnt(14)
	ds_write2_b32 v65, v66, v67 offset1:32
	s_waitcnt lgkmcnt(14)
	ds_write2_b32 v65, v72, v64 offset0:64 offset1:96
	v_add_f32_e32 v64, v77, v242
	v_fmamk_f32 v64, v64, 0x3b800000, v203
	v_rsq_f32_e32 v64, v64
	s_nop 0
	v_mul_f32_e32 v64, v212, v64
	v_mul_f32_e32 v66, v131, v64
	v_mul_f32_e32 v67, v145, v64
	v_mul_f32_e32 v72, v147, v64
	v_mul_f32_e32 v64, v159, v64
	s_waitcnt lgkmcnt(14)
	ds_write2_b32 v65, v66, v67 offset0:128 offset1:160
	s_waitcnt lgkmcnt(14)
	ds_write2_b32 v65, v72, v64 offset0:192 offset1:224
	v_add_u32_e32 v65, 0x2400, v124
	v_add_f32_e32 v64, v78, v244
	v_fmamk_f32 v64, v64, 0x3b800000, v203
	v_rsq_f32_e32 v64, v64
	s_nop 0
	v_mul_f32_e32 v64, v212, v64
	v_mul_f32_e32 v66, v116, v64
	v_mul_f32_e32 v67, v134, v64
	v_mul_f32_e32 v72, v136, v64
	v_mul_f32_e32 v64, v142, v64
	s_waitcnt lgkmcnt(14)
	ds_write2_b32 v65, v66, v67 offset1:32
	s_waitcnt lgkmcnt(14)
	ds_write2_b32 v65, v72, v64 offset0:64 offset1:96
	v_add_f32_e32 v64, v79, v245
	v_fmamk_f32 v64, v64, 0x3b800000, v203
	v_rsq_f32_e32 v64, v64
	s_nop 0
	v_mul_f32_e32 v64, v212, v64
	v_mul_f32_e32 v66, v117, v64
	v_mul_f32_e32 v67, v135, v64
	v_mul_f32_e32 v72, v137, v64
	v_mul_f32_e32 v64, v143, v64
	s_waitcnt lgkmcnt(14)
; __device__ __forceinline__ unsigned cvtpk2(float lo, float hi) { return __builtin_bit_cast(unsigned, __builtin_convertvector((f32x2){lo, hi}, bf16v2)); }
; __device__ __forceinline__ float bf2f(bf16_t b) { return __uint_as_float((unsigned)b << 16); }
; __device__ __forceinline__ float silu_f(float z) { return z * __builtin_amdgcn_rcpf(1.f + __builtin_amdgcn_exp2f(-1.4426950408889634f * z)); }
; template <int LD> ...
;     ...
;   for (int r = 0; r < 16; ++r) { const unsigned cr = (r & 3) + 8 * (r >> 2);
;     const float rs = __builtin_amdgcn_rsqf((ss[r] + xs[(wv ^ 1) * 32 + cr + 4 * hi]) * (1.f / 256.f) + EPS) * epi.oscale;
; #pragma unroll
;     for (int d0 = 0; d0 < 4; ++d0) stg[wb + cr * 128 + d0 * 32] = o[d0][r] * rs; }
;   unsigned rr = (unsigned)(lane >> 4), c8 = (unsigned)(lane & 15) * 8; asm volatile("" : "+v"(rr), "+v"(c8));
;   const unsigned zb = (unsigned)(rb * QBLK + rr) * LD + kh * 128 + c8, ob = (unsigned)(rb * QBLK + rr) * DM + kh * 128 + c8, sb = rr * 128 + c8;
;   const f32x4 sg0 = *(const f32x4*)(epi.sg + kh * 128 + c8), sg1 = *(const f32x4*)(epi.sg + kh * 128 + c8 + 4);
; #pragma unroll
;   for (int i = 0; i < 8; ++i) {
;     const f32x4 a = *(const f32x4*)(stg + sb + i * 512), b = *(const f32x4*)(stg + sb + i * 512 + 4);
;     const bf16x8 zz = *(const bf16x8*)(epi.z0 + zb + (unsigned)(i * 4) * LD);
;     float g[8];
; #pragma unroll
;     for (int k = 0; k < 8; ++k) g[k] = silu_f(bf2f((bf16_t)zz[k]));
;     u32x4 w; w.x = cvtpk2(a[0] * sg0[0] * g[0], a[1] * sg0[1] * g[1]); w.y = cvtpk2(a[2] * sg0[2] * g[2], a[3] * sg0[3] * g[3]);
;     w.z = cvtpk2(b[0] * sg1[0] * g[4], b[1] * sg1[1] * g[5]); w.w = cvtpk2(b[2] * sg1[2] * g[6], b[3] * sg1[3] * g[7]);
;     *(u32x4*)(epi.ao0 + ob + (unsigned)(i * 4) * DM) = w; }
	ds_write2_b32 v65, v66, v67 offset0:128 offset1:160
	s_waitcnt lgkmcnt(14)
	ds_write2_b32 v65, v72, v64 offset0:192 offset1:224
	v_add_u32_e32 v65, 0x3000, v124
	v_add_f32_e32 v64, v68, v246
	v_fmamk_f32 v64, v64, 0x3b800000, v203
	v_rsq_f32_e32 v64, v64
	s_nop 0
	v_mul_f32_e32 v64, v212, v64
	v_mul_f32_e32 v66, v102, v64
	v_mul_f32_e32 v67, v104, v64
	v_mul_f32_e32 v68, v126, v64
	v_mul_f32_e32 v64, v128, v64
	s_waitcnt lgkmcnt(14)
	ds_write2_b32 v65, v66, v67 offset1:32
	s_waitcnt lgkmcnt(14)
	ds_write2_b32 v65, v68, v64 offset0:64 offset1:96
	v_add_f32_e32 v64, v69, v247
	v_fmamk_f32 v64, v64, 0x3b800000, v203
	v_rsq_f32_e32 v64, v64
	s_nop 0
	v_mul_f32_e32 v64, v212, v64
	v_mul_f32_e32 v66, v103, v64
	v_mul_f32_e32 v67, v105, v64
	v_mul_f32_e32 v68, v127, v64
	v_mul_f32_e32 v64, v129, v64
	s_waitcnt lgkmcnt(14)
	ds_write2_b32 v65, v66, v67 offset0:128 offset1:160
	s_waitcnt lgkmcnt(14)
	ds_write2_b32 v65, v68, v64 offset0:192 offset1:224
	v_add_u32_e32 v65, 0x3400, v124
	v_add_f32_e32 v64, v70, v248
	v_fmamk_f32 v64, v64, 0x3b800000, v203
	v_rsq_f32_e32 v64, v64
	s_nop 0
	v_mul_f32_e32 v64, v212, v64
	v_mul_f32_e32 v66, v98, v64
	v_mul_f32_e32 v67, v100, v64
	v_mul_f32_e32 v68, v110, v64
	v_mul_f32_e32 v64, v112, v64
	s_waitcnt lgkmcnt(14)
	ds_write2_b32 v65, v66, v67 offset1:32
	s_waitcnt lgkmcnt(14)
	ds_write2_b32 v65, v68, v64 offset0:64 offset1:96
	v_add_f32_e32 v64, v71, v249
	v_fmamk_f32 v64, v64, 0x3b800000, v203
	v_rsq_f32_e32 v64, v64
	s_nop 0
	v_mul_f32_e32 v64, v212, v64
	v_mul_f32_e32 v66, v99, v64
	v_mul_f32_e32 v67, v101, v64
	v_mul_f32_e32 v68, v111, v64
	v_mul_f32_e32 v64, v113, v64
	s_waitcnt lgkmcnt(14)
	ds_write2_b32 v65, v66, v67 offset0:128 offset1:160
	s_waitcnt lgkmcnt(14)
	ds_write2_b32 v65, v68, v64 offset0:192 offset1:224
	s_waitcnt lgkmcnt(0)
	s_nop 0
	v_add_u32_e32 v73, s36, v213
	v_add_u32_e32 v64, s43, v160
	v_lshl_add_u32 v72, v73, 13, v64
	v_mad_u64_u32 v[78:79], s[24:25], v73, s24, v[72:73]
	v_mov_b32_e32 v73, v161
	v_lshl_add_u64 v[68:69], v[160:161], 2, s[10:11]
	v_lshl_add_u64 v[74:75], v[72:73], 1, s[22:23]
	global_load_dwordx4 v[64:67], v[68:69], off offset:16
	s_nop 0
	global_load_dwordx4 v[68:71], v[68:69], off
	v_lshlrev_b32_e32 v72, 9, v213
	global_load_dwordx4 v[182:185], v[74:75], off
	v_mov_b32_e32 v250, 0x10000
	v_mov_b32_e32 v251, 0
	v_lshl_add_u64 v[254:255], v[74:75], 0, v[250:251]
	global_load_dwordx4 v[186:189], v[254:255], off
	v_lshl_add_u64 v[254:255], v[254:255], 0, v[250:251]
	global_load_dwordx4 v[190:193], v[254:255], off
	v_lshl_add_u64 v[254:255], v[254:255], 0, v[250:251]
	global_load_dwordx4 v[194:197], v[254:255], off
	v_lshl_add_u64 v[254:255], v[254:255], 0, v[250:251]
	global_load_dwordx4 v[198:201], v[254:255], off
	v_lshl_add_u64 v[254:255], v[254:255], 0, v[250:251]
	global_load_dwordx4 v[220:223], v[254:255], off
	v_lshl_add_u64 v[254:255], v[254:255], 0, v[250:251]
	global_load_dwordx4 v[224:227], v[254:255], off
	v_lshl_add_u64 v[254:255], v[254:255], 0, v[250:251]
	global_load_dwordx4 v[228:231], v[254:255], off
	v_lshlrev_b32_e32 v73, 2, v160
	v_add3_u32 v76, s41, v72, v73
	ds_read_b128 v[102:105], v76
	ds_read_b128 v[106:109], v76 offset:16
	v_mov_b32_e32 v79, v161
	v_lshl_add_u64 v[72:73], v[78:79], 1, s[16:17]
	v_add_co_u32_e32 v78, vcc, s65, v74
	s_mov_b32 s24, 0x30000
	s_nop 0
	v_addc_co_u32_e32 v79, vcc, 0, v75, vcc
	s_waitcnt lgkmcnt(0)
	s_waitcnt vmcnt(9)
	v_pk_mul_f32 v[108:109], v[66:67], v[108:109]
	s_waitcnt vmcnt(8)
	v_pk_mul_f32 v[104:105], v[70:71], v[104:105]
	v_pk_mul_f32 v[102:103], v[68:69], v[102:103]
	s_waitcnt vmcnt(7)
	v_and_b32_e32 v111, 0xffff0000, v182
	v_lshlrev_b32_e32 v110, 16, v182
	v_and_b32_e32 v113, 0xffff0000, v183
	v_lshlrev_b32_e32 v112, 16, v183
	v_and_b32_e32 v99, 0xffff0000, v184
	v_lshlrev_b32_e32 v98, 16, v184
	v_and_b32_e32 v115, 0xffff0000, v185
	v_lshlrev_b32_e32 v114, 16, v185
	v_mul_f32_e32 v77, 0xbfb8aa3b, v110
	v_mul_f32_e32 v100, 0xbfb8aa3b, v111
	v_mul_f32_e32 v101, 0xbfb8aa3b, v112
	v_mul_f32_e32 v116, 0xbfb8aa3b, v113
	v_mul_f32_e32 v117, 0xbfb8aa3b, v98
	v_mul_f32_e32 v118, 0xbfb8aa3b, v99
	v_mul_f32_e32 v119, 0xbfb8aa3b, v114
	v_mul_f32_e32 v120, 0xbfb8aa3b, v115
	v_exp_f32_e32 v77, v77
	v_exp_f32_e32 v100, v100
	v_exp_f32_e32 v101, v101
	v_exp_f32_e32 v116, v116
	v_exp_f32_e32 v117, v117
	v_exp_f32_e32 v118, v118
	v_exp_f32_e32 v119, v119
	v_exp_f32_e32 v120, v120
	v_add_f32_e32 v77, 1.0, v77
	v_add_f32_e32 v121, 1.0, v100
	v_add_f32_e32 v122, 1.0, v101
	v_add_f32_e32 v123, 1.0, v116
	v_add_f32_e32 v124, 1.0, v117
	v_add_f32_e32 v125, 1.0, v118
	v_add_f32_e32 v126, 1.0, v119
	v_add_f32_e32 v127, 1.0, v120
	v_rcp_f32_e32 v100, v77
	v_rcp_f32_e32 v101, v121
	v_rcp_f32_e32 v116, v122
	v_rcp_f32_e32 v117, v123
	v_rcp_f32_e32 v118, v124
	v_rcp_f32_e32 v119, v125
	v_rcp_f32_e32 v120, v126
	v_rcp_f32_e32 v121, v127
	v_pk_mul_f32 v[106:107], v[64:65], v[106:107]
	v_pk_mul_f32 v[100:101], v[100:101], v[110:111]
	v_pk_mul_f32 v[110:111], v[116:117], v[112:113]
	v_pk_mul_f32 v[98:99], v[118:119], v[98:99]
	v_pk_mul_f32 v[112:113], v[120:121], v[114:115]
	v_pk_mul_f32 v[100:101], v[102:103], v[100:101]
	v_pk_mul_f32 v[102:103], v[104:105], v[110:111]
	v_pk_mul_f32 v[104:105], v[106:107], v[98:99]
	v_pk_mul_f32 v[106:107], v[108:109], v[112:113]
	v_cvt_pk_bf16_f32 v98, v100, v101
	v_cvt_pk_bf16_f32 v99, v102, v103
	v_cvt_pk_bf16_f32 v100, v104, v105
	v_cvt_pk_bf16_f32 v101, v106, v107
	global_store_dwordx4 v[72:73], v[98:101], off
	ds_read_b128 v[102:105], v76 offset:2048
	ds_read_b128 v[106:109], v76 offset:2064
	v_add_co_u32_e32 v78, vcc, s64, v74
	s_waitcnt lgkmcnt(1)
; __device__ __forceinline__ unsigned cvtpk2(float lo, float hi) { return __builtin_bit_cast(unsigned, __builtin_convertvector((f32x2){lo, hi}, bf16v2)); }
; __device__ __forceinline__ float bf2f(bf16_t b) { return __uint_as_float((unsigned)b << 16); }
; __device__ __forceinline__ float silu_f(float z) { return z * __builtin_amdgcn_rcpf(1.f + __builtin_amdgcn_exp2f(-1.4426950408889634f * z)); }
; template <int LD> ...
;     ...
;   for (int i = 0; i < 8; ++i) {
;     const f32x4 a = *(const f32x4*)(stg + sb + i * 512), b = *(const f32x4*)(stg + sb + i * 512 + 4);
;     const bf16x8 zz = *(const bf16x8*)(epi.z0 + zb + (unsigned)(i * 4) * LD);
;     float g[8];
; #pragma unroll
;     for (int k = 0; k < 8; ++k) g[k] = silu_f(bf2f((bf16_t)zz[k]));
;     u32x4 w; w.x = cvtpk2(a[0] * sg0[0] * g[0], a[1] * sg0[1] * g[1]); w.y = cvtpk2(a[2] * sg0[2] * g[2], a[3] * sg0[3] * g[3]);
;     w.z = cvtpk2(b[0] * sg1[0] * g[4], b[1] * sg1[1] * g[5]); w.w = cvtpk2(b[2] * sg1[2] * g[6], b[3] * sg1[3] * g[7]);
;     *(u32x4*)(epi.ao0 + ob + (unsigned)(i * 4) * DM) = w; }
	v_pk_mul_f32 v[104:105], v[70:71], v[104:105]
	v_addc_co_u32_e32 v79, vcc, 0, v75, vcc
	v_pk_mul_f32 v[102:103], v[68:69], v[102:103]
	s_waitcnt lgkmcnt(0)
	v_pk_mul_f32 v[108:109], v[66:67], v[108:109]
	v_pk_mul_f32 v[106:107], v[64:65], v[106:107]
	v_add_co_u32_e32 v110, vcc, s93, v72
	s_waitcnt vmcnt(7)
	v_and_b32_e32 v113, 0xffff0000, v186
	v_lshlrev_b32_e32 v112, 16, v186
	v_and_b32_e32 v115, 0xffff0000, v187
	v_lshlrev_b32_e32 v114, 16, v187
	v_and_b32_e32 v99, 0xffff0000, v188
	v_lshlrev_b32_e32 v98, 16, v188
	v_and_b32_e32 v117, 0xffff0000, v189
	v_lshlrev_b32_e32 v116, 16, v189
	v_mul_f32_e32 v77, 0xbfb8aa3b, v112
	v_mul_f32_e32 v100, 0xbfb8aa3b, v113
	v_mul_f32_e32 v101, 0xbfb8aa3b, v114
	v_mul_f32_e32 v118, 0xbfb8aa3b, v115
	v_mul_f32_e32 v119, 0xbfb8aa3b, v98
	v_mul_f32_e32 v120, 0xbfb8aa3b, v99
	v_mul_f32_e32 v121, 0xbfb8aa3b, v116
	v_mul_f32_e32 v122, 0xbfb8aa3b, v117
	v_exp_f32_e32 v77, v77
	v_exp_f32_e32 v100, v100
	v_exp_f32_e32 v101, v101
	v_exp_f32_e32 v118, v118
	v_exp_f32_e32 v119, v119
	v_exp_f32_e32 v120, v120
	v_exp_f32_e32 v121, v121
	v_exp_f32_e32 v122, v122
	v_add_f32_e32 v77, 1.0, v77
	v_add_f32_e32 v123, 1.0, v100
	v_add_f32_e32 v124, 1.0, v101
	v_add_f32_e32 v125, 1.0, v118
	v_add_f32_e32 v126, 1.0, v119
	v_add_f32_e32 v127, 1.0, v120
	v_add_f32_e32 v128, 1.0, v121
	v_add_f32_e32 v129, 1.0, v122
	v_rcp_f32_e32 v100, v77
	v_rcp_f32_e32 v101, v123
	v_rcp_f32_e32 v118, v124
	v_rcp_f32_e32 v119, v125
	v_rcp_f32_e32 v120, v126
	v_rcp_f32_e32 v121, v127
	v_rcp_f32_e32 v122, v128
	v_rcp_f32_e32 v123, v129
	v_pk_mul_f32 v[100:101], v[100:101], v[112:113]
	v_pk_mul_f32 v[112:113], v[118:119], v[114:115]
	v_pk_mul_f32 v[98:99], v[120:121], v[98:99]
	v_pk_mul_f32 v[114:115], v[122:123], v[116:117]
	v_pk_mul_f32 v[100:101], v[102:103], v[100:101]
	v_pk_mul_f32 v[102:103], v[104:105], v[112:113]
	v_pk_mul_f32 v[104:105], v[106:107], v[98:99]
	v_pk_mul_f32 v[106:107], v[108:109], v[114:115]
	v_addc_co_u32_e32 v111, vcc, 0, v73, vcc
	v_cvt_pk_bf16_f32 v98, v100, v101
	v_cvt_pk_bf16_f32 v99, v102, v103
	v_cvt_pk_bf16_f32 v100, v104, v105
	v_cvt_pk_bf16_f32 v101, v106, v107
	global_store_dwordx4 v[110:111], v[98:101], off
	ds_read_b128 v[102:105], v76 offset:4096
	ds_read_b128 v[106:109], v76 offset:4112
	v_add_co_u32_e32 v78, vcc, s24, v74
	s_mov_b32 s24, 0x40000
	s_nop 0
	v_addc_co_u32_e32 v79, vcc, 0, v75, vcc
	s_waitcnt lgkmcnt(1)
	v_pk_mul_f32 v[104:105], v[70:71], v[104:105]
	v_pk_mul_f32 v[102:103], v[68:69], v[102:103]
	s_waitcnt lgkmcnt(0)
	v_pk_mul_f32 v[108:109], v[66:67], v[108:109]
	v_pk_mul_f32 v[106:107], v[64:65], v[106:107]
	v_add_co_u32_e32 v110, vcc, s66, v72
	s_waitcnt vmcnt(7)
	v_and_b32_e32 v113, 0xffff0000, v190
	v_lshlrev_b32_e32 v112, 16, v190
	v_and_b32_e32 v115, 0xffff0000, v191
	v_lshlrev_b32_e32 v114, 16, v191
	v_and_b32_e32 v99, 0xffff0000, v192
	v_lshlrev_b32_e32 v98, 16, v192
	v_and_b32_e32 v117, 0xffff0000, v193
	v_lshlrev_b32_e32 v116, 16, v193
	v_mul_f32_e32 v77, 0xbfb8aa3b, v112
	v_mul_f32_e32 v100, 0xbfb8aa3b, v113
	v_mul_f32_e32 v101, 0xbfb8aa3b, v114
	v_mul_f32_e32 v118, 0xbfb8aa3b, v115
	v_mul_f32_e32 v119, 0xbfb8aa3b, v98
	v_mul_f32_e32 v120, 0xbfb8aa3b, v99
	v_mul_f32_e32 v121, 0xbfb8aa3b, v116
	v_mul_f32_e32 v122, 0xbfb8aa3b, v117
	v_exp_f32_e32 v77, v77
	v_exp_f32_e32 v100, v100
	v_exp_f32_e32 v101, v101
	v_exp_f32_e32 v118, v118
	v_exp_f32_e32 v119, v119
	v_exp_f32_e32 v120, v120
	v_exp_f32_e32 v121, v121
	v_exp_f32_e32 v122, v122
	v_add_f32_e32 v77, 1.0, v77
	v_add_f32_e32 v123, 1.0, v100
	v_add_f32_e32 v124, 1.0, v101
	v_add_f32_e32 v125, 1.0, v118
	v_add_f32_e32 v126, 1.0, v119
	v_add_f32_e32 v127, 1.0, v120
	v_add_f32_e32 v128, 1.0, v121
	v_add_f32_e32 v129, 1.0, v122
	v_rcp_f32_e32 v100, v77
	v_rcp_f32_e32 v101, v123
	v_rcp_f32_e32 v118, v124
	v_rcp_f32_e32 v119, v125
	v_rcp_f32_e32 v120, v126
	v_rcp_f32_e32 v121, v127
	v_rcp_f32_e32 v122, v128
	v_rcp_f32_e32 v123, v129
	v_pk_mul_f32 v[100:101], v[100:101], v[112:113]
	v_pk_mul_f32 v[112:113], v[118:119], v[114:115]
	v_pk_mul_f32 v[98:99], v[120:121], v[98:99]
	v_pk_mul_f32 v[114:115], v[122:123], v[116:117]
	v_pk_mul_f32 v[100:101], v[102:103], v[100:101]
	v_pk_mul_f32 v[102:103], v[104:105], v[112:113]
	v_pk_mul_f32 v[104:105], v[106:107], v[98:99]
	v_pk_mul_f32 v[106:107], v[108:109], v[114:115]
	v_addc_co_u32_e32 v111, vcc, 0, v73, vcc
	v_cvt_pk_bf16_f32 v98, v100, v101
	v_cvt_pk_bf16_f32 v99, v102, v103
	v_cvt_pk_bf16_f32 v100, v104, v105
	v_cvt_pk_bf16_f32 v101, v106, v107
	global_store_dwordx4 v[110:111], v[98:101], off
	ds_read_b128 v[102:105], v76 offset:6144
	ds_read_b128 v[106:109], v76 offset:6160
	v_add_co_u32_e32 v78, vcc, s24, v74
	s_mov_b32 s24, 0x50000
	s_nop 0
	v_addc_co_u32_e32 v79, vcc, 0, v75, vcc
	s_waitcnt lgkmcnt(1)
	v_pk_mul_f32 v[104:105], v[70:71], v[104:105]
	v_pk_mul_f32 v[102:103], v[68:69], v[102:103]
	s_waitcnt lgkmcnt(0)
	v_pk_mul_f32 v[108:109], v[66:67], v[108:109]
	v_pk_mul_f32 v[106:107], v[64:65], v[106:107]
	v_add_co_u32_e32 v110, vcc, s95, v72
	s_waitcnt vmcnt(7)
; __device__ __forceinline__ unsigned cvtpk2(float lo, float hi) { return __builtin_bit_cast(unsigned, __builtin_convertvector((f32x2){lo, hi}, bf16v2)); }
; __device__ __forceinline__ float bf2f(bf16_t b) { return __uint_as_float((unsigned)b << 16); }
; __device__ __forceinline__ float silu_f(float z) { return z * __builtin_amdgcn_rcpf(1.f + __builtin_amdgcn_exp2f(-1.4426950408889634f * z)); }
; template <int LD> ...
;     ...
;   for (int i = 0; i < 8; ++i) {
;     const f32x4 a = *(const f32x4*)(stg + sb + i * 512), b = *(const f32x4*)(stg + sb + i * 512 + 4);
;     const bf16x8 zz = *(const bf16x8*)(epi.z0 + zb + (unsigned)(i * 4) * LD);
;     float g[8];
; #pragma unroll
;     for (int k = 0; k < 8; ++k) g[k] = silu_f(bf2f((bf16_t)zz[k]));
;     u32x4 w; w.x = cvtpk2(a[0] * sg0[0] * g[0], a[1] * sg0[1] * g[1]); w.y = cvtpk2(a[2] * sg0[2] * g[2], a[3] * sg0[3] * g[3]);
;     w.z = cvtpk2(b[0] * sg1[0] * g[4], b[1] * sg1[1] * g[5]); w.w = cvtpk2(b[2] * sg1[2] * g[6], b[3] * sg1[3] * g[7]);
;     *(u32x4*)(epi.ao0 + ob + (unsigned)(i * 4) * DM) = w; }
	v_and_b32_e32 v113, 0xffff0000, v194
	v_lshlrev_b32_e32 v112, 16, v194
	v_and_b32_e32 v115, 0xffff0000, v195
	v_lshlrev_b32_e32 v114, 16, v195
	v_and_b32_e32 v99, 0xffff0000, v196
	v_lshlrev_b32_e32 v98, 16, v196
	v_and_b32_e32 v117, 0xffff0000, v197
	v_lshlrev_b32_e32 v116, 16, v197
	v_mul_f32_e32 v77, 0xbfb8aa3b, v112
	v_mul_f32_e32 v100, 0xbfb8aa3b, v113
	v_mul_f32_e32 v101, 0xbfb8aa3b, v114
	v_mul_f32_e32 v118, 0xbfb8aa3b, v115
	v_mul_f32_e32 v119, 0xbfb8aa3b, v98
	v_mul_f32_e32 v120, 0xbfb8aa3b, v99
	v_mul_f32_e32 v121, 0xbfb8aa3b, v116
	v_mul_f32_e32 v122, 0xbfb8aa3b, v117
	v_exp_f32_e32 v77, v77
	v_exp_f32_e32 v100, v100
	v_exp_f32_e32 v101, v101
	v_exp_f32_e32 v118, v118
	v_exp_f32_e32 v119, v119
	v_exp_f32_e32 v120, v120
	v_exp_f32_e32 v121, v121
	v_exp_f32_e32 v122, v122
	v_add_f32_e32 v77, 1.0, v77
	v_add_f32_e32 v123, 1.0, v100
	v_add_f32_e32 v124, 1.0, v101
	v_add_f32_e32 v125, 1.0, v118
	v_add_f32_e32 v126, 1.0, v119
	v_add_f32_e32 v127, 1.0, v120
	v_add_f32_e32 v128, 1.0, v121
	v_add_f32_e32 v129, 1.0, v122
	v_rcp_f32_e32 v100, v77
	v_rcp_f32_e32 v101, v123
	v_rcp_f32_e32 v118, v124
	v_rcp_f32_e32 v119, v125
	v_rcp_f32_e32 v120, v126
	v_rcp_f32_e32 v121, v127
	v_rcp_f32_e32 v122, v128
	v_rcp_f32_e32 v123, v129
	v_pk_mul_f32 v[100:101], v[100:101], v[112:113]
	v_pk_mul_f32 v[112:113], v[118:119], v[114:115]
	v_pk_mul_f32 v[98:99], v[120:121], v[98:99]
	v_pk_mul_f32 v[114:115], v[122:123], v[116:117]
	v_pk_mul_f32 v[100:101], v[102:103], v[100:101]
	v_pk_mul_f32 v[102:103], v[104:105], v[112:113]
	v_pk_mul_f32 v[104:105], v[106:107], v[98:99]
	v_pk_mul_f32 v[106:107], v[108:109], v[114:115]
	v_addc_co_u32_e32 v111, vcc, 0, v73, vcc
	v_cvt_pk_bf16_f32 v98, v100, v101
	v_cvt_pk_bf16_f32 v99, v102, v103
	v_cvt_pk_bf16_f32 v100, v104, v105
	v_cvt_pk_bf16_f32 v101, v106, v107
	global_store_dwordx4 v[110:111], v[98:101], off
	ds_read_b128 v[102:105], v76 offset:8192
	ds_read_b128 v[106:109], v76 offset:8208
	v_add_co_u32_e32 v78, vcc, s24, v74
	s_mov_b32 s24, 0x60000
	s_nop 0
	v_addc_co_u32_e32 v79, vcc, 0, v75, vcc
	s_waitcnt lgkmcnt(1)
	v_pk_mul_f32 v[104:105], v[70:71], v[104:105]
	v_pk_mul_f32 v[102:103], v[68:69], v[102:103]
	s_waitcnt lgkmcnt(0)
	v_pk_mul_f32 v[108:109], v[66:67], v[108:109]
	v_pk_mul_f32 v[106:107], v[64:65], v[106:107]
	v_add_co_u32_e32 v110, vcc, s65, v72
	s_waitcnt vmcnt(7)
	v_and_b32_e32 v113, 0xffff0000, v198
	v_lshlrev_b32_e32 v112, 16, v198
	v_and_b32_e32 v115, 0xffff0000, v199
	v_lshlrev_b32_e32 v114, 16, v199
	v_and_b32_e32 v99, 0xffff0000, v200
	v_lshlrev_b32_e32 v98, 16, v200
	v_and_b32_e32 v117, 0xffff0000, v201
	v_lshlrev_b32_e32 v116, 16, v201
	v_mul_f32_e32 v77, 0xbfb8aa3b, v112
	v_mul_f32_e32 v100, 0xbfb8aa3b, v113
	v_mul_f32_e32 v101, 0xbfb8aa3b, v114
	v_mul_f32_e32 v118, 0xbfb8aa3b, v115
	v_mul_f32_e32 v119, 0xbfb8aa3b, v98
	v_mul_f32_e32 v120, 0xbfb8aa3b, v99
	v_mul_f32_e32 v121, 0xbfb8aa3b, v116
	v_mul_f32_e32 v122, 0xbfb8aa3b, v117
	v_exp_f32_e32 v77, v77
	v_exp_f32_e32 v100, v100
	v_exp_f32_e32 v101, v101
	v_exp_f32_e32 v118, v118
	v_exp_f32_e32 v119, v119
	v_exp_f32_e32 v120, v120
	v_exp_f32_e32 v121, v121
	v_exp_f32_e32 v122, v122
	v_add_f32_e32 v77, 1.0, v77
	v_add_f32_e32 v123, 1.0, v100
	v_add_f32_e32 v124, 1.0, v101
	v_add_f32_e32 v125, 1.0, v118
	v_add_f32_e32 v126, 1.0, v119
	v_add_f32_e32 v127, 1.0, v120
	v_add_f32_e32 v128, 1.0, v121
	v_add_f32_e32 v129, 1.0, v122
	v_rcp_f32_e32 v100, v77
	v_rcp_f32_e32 v101, v123
	v_rcp_f32_e32 v118, v124
	v_rcp_f32_e32 v119, v125
	v_rcp_f32_e32 v120, v126
	v_rcp_f32_e32 v121, v127
	v_rcp_f32_e32 v122, v128
	v_rcp_f32_e32 v123, v129
	v_pk_mul_f32 v[100:101], v[100:101], v[112:113]
	v_pk_mul_f32 v[112:113], v[118:119], v[114:115]
	v_pk_mul_f32 v[98:99], v[120:121], v[98:99]
	v_pk_mul_f32 v[114:115], v[122:123], v[116:117]
	v_pk_mul_f32 v[100:101], v[102:103], v[100:101]
	v_pk_mul_f32 v[102:103], v[104:105], v[112:113]
	v_pk_mul_f32 v[104:105], v[106:107], v[98:99]
	v_pk_mul_f32 v[106:107], v[108:109], v[114:115]
	v_addc_co_u32_e32 v111, vcc, 0, v73, vcc
	v_cvt_pk_bf16_f32 v98, v100, v101
	v_cvt_pk_bf16_f32 v99, v102, v103
	v_cvt_pk_bf16_f32 v100, v104, v105
	v_cvt_pk_bf16_f32 v101, v106, v107
	global_store_dwordx4 v[110:111], v[98:101], off
	ds_read_b128 v[102:105], v76 offset:10240
	ds_read_b128 v[106:109], v76 offset:10256
	v_add_co_u32_e32 v78, vcc, s24, v74
	s_mov_b32 s24, 0x14000
	s_nop 0
	v_addc_co_u32_e32 v79, vcc, 0, v75, vcc
	s_waitcnt lgkmcnt(1)
	v_pk_mul_f32 v[104:105], v[70:71], v[104:105]
	v_pk_mul_f32 v[102:103], v[68:69], v[102:103]
	s_waitcnt lgkmcnt(0)
	v_pk_mul_f32 v[108:109], v[66:67], v[108:109]
	v_pk_mul_f32 v[106:107], v[64:65], v[106:107]
	v_add_co_u32_e32 v110, vcc, s24, v72
	s_mov_b32 s24, 0x70000
	s_nop 0
	v_addc_co_u32_e32 v111, vcc, 0, v73, vcc
	v_add_co_u32_e32 v74, vcc, s24, v74
	s_mov_b32 s24, 0x18000
	s_nop 0
	v_addc_co_u32_e32 v75, vcc, 0, v75, vcc
	s_waitcnt vmcnt(7)
; __device__ __forceinline__ unsigned cvtpk2(float lo, float hi) { return __builtin_bit_cast(unsigned, __builtin_convertvector((f32x2){lo, hi}, bf16v2)); }
; __device__ __forceinline__ float bf2f(bf16_t b) { return __uint_as_float((unsigned)b << 16); }
; __device__ __forceinline__ float silu_f(float z) { return z * __builtin_amdgcn_rcpf(1.f + __builtin_amdgcn_exp2f(-1.4426950408889634f * z)); }
; template <int LD> ...
;     ...
;   for (int i = 0; i < 8; ++i) {
;     const f32x4 a = *(const f32x4*)(stg + sb + i * 512), b = *(const f32x4*)(stg + sb + i * 512 + 4);
;     const bf16x8 zz = *(const bf16x8*)(epi.z0 + zb + (unsigned)(i * 4) * LD);
;     float g[8];
; #pragma unroll
;     for (int k = 0; k < 8; ++k) g[k] = silu_f(bf2f((bf16_t)zz[k]));
;     u32x4 w; w.x = cvtpk2(a[0] * sg0[0] * g[0], a[1] * sg0[1] * g[1]); w.y = cvtpk2(a[2] * sg0[2] * g[2], a[3] * sg0[3] * g[3]);
;     w.z = cvtpk2(b[0] * sg1[0] * g[4], b[1] * sg1[1] * g[5]); w.w = cvtpk2(b[2] * sg1[2] * g[6], b[3] * sg1[3] * g[7]);
;     *(u32x4*)(epi.ao0 + ob + (unsigned)(i * 4) * DM) = w; }
;   __syncthreads();
	v_and_b32_e32 v113, 0xffff0000, v220
	v_lshlrev_b32_e32 v112, 16, v220
	v_and_b32_e32 v115, 0xffff0000, v221
	v_lshlrev_b32_e32 v114, 16, v221
	v_and_b32_e32 v99, 0xffff0000, v222
	v_lshlrev_b32_e32 v98, 16, v222
	v_and_b32_e32 v117, 0xffff0000, v223
	v_lshlrev_b32_e32 v116, 16, v223
	v_mul_f32_e32 v77, 0xbfb8aa3b, v112
	v_mul_f32_e32 v100, 0xbfb8aa3b, v113
	v_mul_f32_e32 v101, 0xbfb8aa3b, v114
	v_mul_f32_e32 v118, 0xbfb8aa3b, v115
	v_mul_f32_e32 v119, 0xbfb8aa3b, v98
	v_mul_f32_e32 v120, 0xbfb8aa3b, v99
	v_mul_f32_e32 v121, 0xbfb8aa3b, v116
	v_mul_f32_e32 v122, 0xbfb8aa3b, v117
	v_exp_f32_e32 v77, v77
	v_exp_f32_e32 v100, v100
	v_exp_f32_e32 v101, v101
	v_exp_f32_e32 v118, v118
	v_exp_f32_e32 v119, v119
	v_exp_f32_e32 v120, v120
	v_exp_f32_e32 v121, v121
	v_exp_f32_e32 v122, v122
	v_add_f32_e32 v77, 1.0, v77
	v_add_f32_e32 v123, 1.0, v100
	v_add_f32_e32 v124, 1.0, v101
	v_add_f32_e32 v125, 1.0, v118
	v_add_f32_e32 v126, 1.0, v119
	v_add_f32_e32 v127, 1.0, v120
	v_add_f32_e32 v128, 1.0, v121
	v_add_f32_e32 v129, 1.0, v122
	v_rcp_f32_e32 v100, v77
	v_rcp_f32_e32 v101, v123
	v_rcp_f32_e32 v118, v124
	v_rcp_f32_e32 v119, v125
	v_rcp_f32_e32 v120, v126
	v_rcp_f32_e32 v121, v127
	v_rcp_f32_e32 v122, v128
	v_rcp_f32_e32 v123, v129
	v_pk_mul_f32 v[100:101], v[100:101], v[112:113]
	v_pk_mul_f32 v[112:113], v[118:119], v[114:115]
	v_pk_mul_f32 v[98:99], v[120:121], v[98:99]
	v_pk_mul_f32 v[114:115], v[122:123], v[116:117]
	v_pk_mul_f32 v[100:101], v[102:103], v[100:101]
	v_pk_mul_f32 v[102:103], v[104:105], v[112:113]
	v_pk_mul_f32 v[104:105], v[106:107], v[98:99]
	v_pk_mul_f32 v[106:107], v[108:109], v[114:115]
	v_cvt_pk_bf16_f32 v98, v100, v101
	v_cvt_pk_bf16_f32 v99, v102, v103
	v_cvt_pk_bf16_f32 v100, v104, v105
	v_cvt_pk_bf16_f32 v101, v106, v107
	global_store_dwordx4 v[110:111], v[98:101], off
	ds_read_b128 v[102:105], v76 offset:12288
	ds_read_b128 v[106:109], v76 offset:12304
	v_add_co_u32_e32 v78, vcc, s24, v72
	s_waitcnt lgkmcnt(1)
	v_pk_mul_f32 v[104:105], v[70:71], v[104:105]
	v_pk_mul_f32 v[102:103], v[68:69], v[102:103]
	s_waitcnt lgkmcnt(0)
	v_pk_mul_f32 v[108:109], v[66:67], v[108:109]
	v_pk_mul_f32 v[106:107], v[64:65], v[106:107]
	v_addc_co_u32_e32 v79, vcc, 0, v73, vcc
	v_add_co_u32_e32 v72, vcc, 0x1c000, v72
	s_waitcnt vmcnt(7)
	v_and_b32_e32 v111, 0xffff0000, v224
	v_lshlrev_b32_e32 v110, 16, v224
	v_and_b32_e32 v113, 0xffff0000, v225
	v_lshlrev_b32_e32 v112, 16, v225
	v_and_b32_e32 v99, 0xffff0000, v226
	v_lshlrev_b32_e32 v98, 16, v226
	v_and_b32_e32 v115, 0xffff0000, v227
	v_lshlrev_b32_e32 v114, 16, v227
	v_mul_f32_e32 v77, 0xbfb8aa3b, v110
	v_mul_f32_e32 v100, 0xbfb8aa3b, v111
	v_mul_f32_e32 v101, 0xbfb8aa3b, v112
	v_mul_f32_e32 v116, 0xbfb8aa3b, v113
	v_mul_f32_e32 v117, 0xbfb8aa3b, v98
	v_mul_f32_e32 v118, 0xbfb8aa3b, v99
	v_mul_f32_e32 v119, 0xbfb8aa3b, v114
	v_mul_f32_e32 v120, 0xbfb8aa3b, v115
	v_exp_f32_e32 v77, v77
	v_exp_f32_e32 v100, v100
	v_exp_f32_e32 v101, v101
	v_exp_f32_e32 v116, v116
	v_exp_f32_e32 v117, v117
	v_exp_f32_e32 v118, v118
	v_exp_f32_e32 v119, v119
	v_exp_f32_e32 v120, v120
	v_add_f32_e32 v77, 1.0, v77
	v_add_f32_e32 v121, 1.0, v100
	v_add_f32_e32 v122, 1.0, v101
	v_add_f32_e32 v123, 1.0, v116
	v_add_f32_e32 v124, 1.0, v117
	v_add_f32_e32 v125, 1.0, v118
	v_add_f32_e32 v126, 1.0, v119
	v_add_f32_e32 v127, 1.0, v120
	v_rcp_f32_e32 v100, v77
	v_rcp_f32_e32 v101, v121
	v_rcp_f32_e32 v116, v122
	v_rcp_f32_e32 v117, v123
	v_rcp_f32_e32 v118, v124
	v_rcp_f32_e32 v119, v125
	v_rcp_f32_e32 v120, v126
	v_rcp_f32_e32 v121, v127
	v_pk_mul_f32 v[100:101], v[100:101], v[110:111]
	v_pk_mul_f32 v[110:111], v[116:117], v[112:113]
	v_pk_mul_f32 v[98:99], v[118:119], v[98:99]
	v_pk_mul_f32 v[112:113], v[120:121], v[114:115]
	v_pk_mul_f32 v[100:101], v[102:103], v[100:101]
	v_pk_mul_f32 v[102:103], v[104:105], v[110:111]
	v_pk_mul_f32 v[104:105], v[106:107], v[98:99]
	v_pk_mul_f32 v[106:107], v[108:109], v[112:113]
	v_cvt_pk_bf16_f32 v98, v100, v101
	v_cvt_pk_bf16_f32 v99, v102, v103
	v_cvt_pk_bf16_f32 v100, v104, v105
	v_cvt_pk_bf16_f32 v101, v106, v107
	global_store_dwordx4 v[78:79], v[98:101], off
	ds_read_b128 v[102:105], v76 offset:14336
	ds_read_b128 v[74:77], v76 offset:14352
	v_addc_co_u32_e32 v73, vcc, 0, v73, vcc
	s_waitcnt lgkmcnt(1)
	v_pk_mul_f32 v[70:71], v[70:71], v[104:105]
	s_waitcnt lgkmcnt(0)
	v_pk_mul_f32 v[66:67], v[66:67], v[76:77]
	v_pk_mul_f32 v[64:65], v[64:65], v[74:75]
	v_pk_mul_f32 v[68:69], v[68:69], v[102:103]
	s_waitcnt vmcnt(7)
	v_and_b32_e32 v75, 0xffff0000, v228
	v_lshlrev_b32_e32 v74, 16, v228
	v_and_b32_e32 v77, 0xffff0000, v229
	v_lshlrev_b32_e32 v76, 16, v229
	v_and_b32_e32 v79, 0xffff0000, v230
	v_lshlrev_b32_e32 v78, 16, v230
	v_and_b32_e32 v99, 0xffff0000, v231
	v_lshlrev_b32_e32 v98, 16, v231
	v_mul_f32_e32 v100, 0xbfb8aa3b, v74
	v_mul_f32_e32 v101, 0xbfb8aa3b, v75
	v_mul_f32_e32 v102, 0xbfb8aa3b, v76
	v_mul_f32_e32 v103, 0xbfb8aa3b, v77
	v_mul_f32_e32 v104, 0xbfb8aa3b, v78
	v_mul_f32_e32 v105, 0xbfb8aa3b, v79
	v_mul_f32_e32 v106, 0xbfb8aa3b, v98
	v_mul_f32_e32 v107, 0xbfb8aa3b, v99
	v_exp_f32_e32 v100, v100
	v_exp_f32_e32 v101, v101
	v_exp_f32_e32 v102, v102
	v_exp_f32_e32 v103, v103
	v_exp_f32_e32 v104, v104
	v_exp_f32_e32 v105, v105
	v_exp_f32_e32 v106, v106
	v_exp_f32_e32 v107, v107
	v_add_f32_e32 v100, 1.0, v100
	v_add_f32_e32 v101, 1.0, v101
	v_add_f32_e32 v102, 1.0, v102
	v_add_f32_e32 v103, 1.0, v103
	v_add_f32_e32 v104, 1.0, v104
	v_add_f32_e32 v105, 1.0, v105
	v_add_f32_e32 v106, 1.0, v106
	v_add_f32_e32 v107, 1.0, v107
	v_rcp_f32_e32 v100, v100
	v_rcp_f32_e32 v101, v101
	v_rcp_f32_e32 v102, v102
	v_rcp_f32_e32 v103, v103
	v_rcp_f32_e32 v104, v104
	v_rcp_f32_e32 v105, v105
	v_rcp_f32_e32 v106, v106
	v_rcp_f32_e32 v107, v107
	v_pk_mul_f32 v[74:75], v[100:101], v[74:75]
	v_pk_mul_f32 v[76:77], v[102:103], v[76:77]
	v_pk_mul_f32 v[78:79], v[104:105], v[78:79]
	v_pk_mul_f32 v[98:99], v[106:107], v[98:99]
	v_pk_mul_f32 v[68:69], v[68:69], v[74:75]
	v_pk_mul_f32 v[70:71], v[70:71], v[76:77]
	v_pk_mul_f32 v[74:75], v[64:65], v[78:79]
	v_pk_mul_f32 v[76:77], v[66:67], v[98:99]
	v_cvt_pk_bf16_f32 v64, v68, v69
	v_cvt_pk_bf16_f32 v65, v70, v71
	v_cvt_pk_bf16_f32 v66, v74, v75
	v_cvt_pk_bf16_f32 v67, v76, v77
	global_store_dwordx4 v[72:73], v[64:67], off
	s_barrier
	s_branch .LBB0_20
